# v34: v29 + removed compiler-inserted vmcnt(0) LDS-DMA alias drains before ds_reads in the S5-Y gemm k-loop (DMA of next k-step now overlaps compute)
# speedup vs baseline: 1.0325x; 1.0128x over previous
; #define VBID ((int)(blockIdx.x * 2 + (otid() >> 8)))
; #define LAS __attribute__((address_space(3)))
; template <class FA, class FB, class FL, class FS>
; DI void gemm_tile(char* lds, int ksteps, int rot, FA fa, FB fb, FL fl, FS fs) {
;     ...
; #pragma unroll
;   for (int i = 0; i < 4; ++i) {
;     const int id = tid + i * 256, r = id >> 3, c = (id & 7) ^ (r & 7);
;     __builtin_amdgcn_global_load_lds((const unsigned*)fa(r, rot * 8 + c), (LAS unsigned*)(l3 + id * 16), 16, 0, 0);
;     __builtin_amdgcn_global_load_lds((const unsigned*)fb(r, rot * 8 + c), (LAS unsigned*)(l3 + 16384 + id * 16), 16, 0, 0);
;   }
;   asm volatile("s_waitcnt vmcnt(0)" ::: "memory");
;   __syncthreads();
; DI void phase_s5_y(const Params& p, char* lds) {
;     ...
;     int L = k_ * VGRID + VBID; const bool active_ = L < (nt); if (!active_) L = (nt) - 1;
;     const int j = 3 - (L >> 10), rem = L & 1023, g = rem >> 4, mt = rem & 15;
;     const bf16_t* Ug = ugm + (size_t)g * MP * 16 + (size_t)mt * 128 * 512;
;     const bf16_t* Hg = H + ((size_t)g * 2048 + mt * 128) * 128;
;     gemm_tile(lds, 2 + 2 * (j + 1), 0,
;       [&](int r, int kc) { return kc < 16 ? Hg + (size_t)r * 128 + kc * 8 : Ug + (size_t)r * 512 + (kc - 16) * 8; },
.LBB0_625:
	v_mov_b32_e32 v0, v182
	v_readlane_b32 s1, v251, 7
	v_ashrrev_i32_e32 v0, 8, v0
	s_add_i32 s0, s0, s1
	v_add_u32_e32 v0, s0, v0
	v_min_i32_e32 v0, 0xfff, v0
	v_and_b32_e32 v70, 0x600, v0
	v_and_b32_e32 v71, 0x800, v0
	v_and_b32_e32 v0, 0x1ff, v0
	v_lshl_or_b32 v0, v70, 1, v0
	v_lshrrev_b32_e32 v71, 2, v71
	v_or_b32_e32 v0, v0, v71
	v_bfe_u32 v70, v0, 4, 6
	v_and_b32_e32 v71, 15, v0
	v_lshlrev_b32_e32 v68, 19, v70
	v_mov_b32_e32 v26, v182
	v_ashrrev_i32_e32 v154, 10, v0
	v_lshl_add_u64 v[0:1], s[8:9], 0, v[68:69]
	v_lshlrev_b32_e32 v68, 15, v71
	v_lshl_add_u64 v[6:7], v[0:1], 0, v[68:69]
	v_bfe_u32 v24, v26, 3, 5
	v_xor_b32_e32 v0, v24, v26
	v_lshlrev_b32_sdwa v82, v103, v26 dst_sel:DWORD dst_unused:UNUSED_PAD src0_sel:DWORD src1_sel:BYTE_0
	v_lshlrev_b32_e32 v68, 8, v24
	v_lshlrev_b32_e32 v0, 4, v0
	v_add_u32_e32 v56, v102, v82
	v_sub_u32_e32 v91, 3, v154
	v_lshl_add_u64 v[8:9], v[6:7], 0, v[68:69]
	v_and_b32_e32 v68, 0x70, v0
	v_readfirstlane_b32 s0, v56
	v_lshl_add_u64 v[0:1], v[8:9], 0, v[68:69]
	s_mov_b32 m0, s0
	v_lshlrev_b32_e32 v81, 7, v91
	global_load_lds_dwordx4 v[0:1], off
	v_or_b32_e32 v0, v81, v24
	v_mov_b32_e32 v1, v69
	v_lshlrev_b32_e32 v2, 17, v70
	v_mov_b32_e32 v3, v69
	v_lshl_add_u64 v[10:11], s[10:11], 0, v[2:3]
	v_lshlrev_b64 v[2:3], 8, v[0:1]
	v_add_u32_e32 v1, 0x4000, v56
	v_lshl_add_u64 v[22:23], v[10:11], 0, v[2:3]
	v_readfirstlane_b32 s0, v1
	v_or_b32_sdwa v1, v26, s33 dst_sel:DWORD dst_unused:UNUSED_PAD src0_sel:BYTE_0 src1_sel:DWORD
	v_lshl_add_u64 v[2:3], v[22:23], 0, v[68:69]
	s_mov_b32 m0, s0
	v_lshrrev_b32_e32 v155, 3, v1
	global_load_lds_dwordx4 v[2:3], off
	v_xor_b32_e32 v2, v155, v26
	v_lshlrev_b32_e32 v83, 4, v1
	v_lshlrev_b32_e32 v68, 8, v155
	v_lshlrev_b32_e32 v2, 4, v2
	v_add_u32_e32 v1, v102, v83
	v_lshl_add_u64 v[60:61], v[6:7], 0, v[68:69]
	v_and_b32_e32 v68, 0x70, v2
	v_readfirstlane_b32 s0, v1
	v_lshl_add_u64 v[2:3], v[60:61], 0, v[68:69]
	s_mov_b32 m0, s0
	v_lshrrev_b32_e32 v80, 4, v26
	global_load_lds_dwordx4 v[2:3], off
	v_or_b32_e32 v2, v81, v155
	v_mov_b32_e32 v3, v69
	v_lshlrev_b64 v[4:5], 8, v[2:3]
	v_add_u32_e32 v3, 0x4000, v1
	v_lshl_add_u64 v[62:63], v[10:11], 0, v[4:5]
	v_readfirstlane_b32 s0, v3
	v_or_b32_sdwa v3, v26, s34 dst_sel:DWORD dst_unused:UNUSED_PAD src0_sel:BYTE_0 src1_sel:DWORD
	v_lshl_add_u64 v[4:5], v[62:63], 0, v[68:69]
	s_mov_b32 m0, s0
	v_lshrrev_b32_e32 v156, 3, v3
	global_load_lds_dwordx4 v[4:5], off
	v_xor_b32_e32 v4, v156, v26
	v_lshlrev_b32_e32 v84, 4, v3
	v_lshlrev_b32_e32 v68, 8, v156
	v_lshlrev_b32_e32 v4, 4, v4
	v_add_u32_e32 v3, v102, v84
	v_lshl_add_u64 v[64:65], v[6:7], 0, v[68:69]
	v_and_b32_e32 v68, 0x70, v4
	v_readfirstlane_b32 s0, v3
	v_lshl_add_u64 v[4:5], v[64:65], 0, v[68:69]
	s_mov_b32 m0, s0
	v_and_b32_e32 v25, 7, v26
	global_load_lds_dwordx4 v[4:5], off
	v_or_b32_e32 v4, v81, v156
	v_mov_b32_e32 v5, v69
	v_lshlrev_b64 v[12:13], 8, v[4:5]
	v_add_u32_e32 v5, 0x4000, v3
	v_lshl_add_u64 v[76:77], v[10:11], 0, v[12:13]
	v_readfirstlane_b32 s0, v5
	v_or_b32_sdwa v5, v26, s35 dst_sel:DWORD dst_unused:UNUSED_PAD src0_sel:BYTE_0 src1_sel:DWORD
	v_lshl_add_u64 v[12:13], v[76:77], 0, v[68:69]
	s_mov_b32 m0, s0
	v_lshrrev_b32_e32 v157, 3, v5
	global_load_lds_dwordx4 v[12:13], off
	v_xor_b32_e32 v12, v157, v26
	v_lshlrev_b32_e32 v68, 8, v157
	v_lshlrev_b32_e32 v85, 4, v5
	v_lshl_add_u64 v[100:101], v[6:7], 0, v[68:69]
	v_lshlrev_b32_e32 v6, 4, v12
	v_add_u32_e32 v5, v102, v85
	v_and_b32_e32 v68, 0x70, v6
	v_readfirstlane_b32 s0, v5
	v_lshl_add_u64 v[6:7], v[100:101], 0, v[68:69]
	s_mov_b32 m0, s0
	v_and_b32_e32 v79, 15, v26
	global_load_lds_dwordx4 v[6:7], off
	v_or_b32_e32 v6, v81, v157
	v_mov_b32_e32 v7, v69
	v_lshlrev_b64 v[12:13], 8, v[6:7]
	v_add_u32_e32 v7, 0x4000, v5
	v_lshl_add_u64 v[148:149], v[10:11], 0, v[12:13]
	v_readfirstlane_b32 s0, v7
	v_lshl_add_u64 v[10:11], v[148:149], 0, v[68:69]
	s_mov_b32 m0, s0
	v_lshlrev_b32_e32 v68, 21, v70
	global_load_lds_dwordx4 v[10:11], off
	v_lshl_add_u64 v[10:11], s[6:7], 0, v[68:69]
	v_lshlrev_b32_e32 v68, 17, v71
	v_bfe_u32 v7, v26, 4, 2
	v_lshl_add_u64 v[152:153], v[10:11], 0, v[68:69]
	v_bitop3_b32 v10, v80, v25, 3 bitop3:0x6c
	v_bitop3_b32 v7, v7, v25, 4 bitop3:0x36
	v_bfe_u32 v78, v26, 6, 1
	v_bfe_u32 v86, v26, 7, 1
	v_lshlrev_b32_e32 v87, 4, v10
	v_lshlrev_b32_e32 v14, 7, v79
	v_lshlrev_b32_e32 v90, 4, v7
	v_lshlrev_b32_e32 v7, 7, v26
	v_lshl_or_b32 v88, v78, 13, v14
	v_add_u32_e32 v15, v102, v87
	v_lshl_or_b32 v89, v86, 13, v14
	v_lshlrev_b32_e32 v68, 10, v24
	v_and_b32_e32 v7, 0x3c00, v7
	v_bitop3_b32 v158, v24, 7, v26 bitop3:0x48
	v_add_u32_e32 v27, v15, v88
	v_add_u32_e32 v57, v15, v89
	v_lshl_add_u64 v[24:25], v[152:153], 0, v[68:69]
	v_lshl_or_b32 v68, v70, 14, v7
	s_waitcnt vmcnt(0)
	s_waitcnt vmcnt(0) lgkmcnt(0)
	s_barrier
; #define MFMA16(a, b, c) __builtin_amdgcn_mfma_f32_16x16x32_bf16((a), (b), (c), 0, 0, 0)
; #define LAS __attribute__((address_space(3)))
; template <class FA, class FB, class FL, class FS>
; DI void gemm_tile(char* lds, int ksteps, int rot, FA fa, FB fb, FL fl, FS fs) {
;     ...
;   for (int ks = 0; ks < ksteps; ++ks) {
;     const int cur = ks & 1;
;     if (ks + 1 < ksteps) {
;       int kn = ks + 1 + rot; if (kn >= ksteps) kn -= ksteps;
;       LAS char* dst = l3 + (cur ^ 1) * 32768;
; #pragma unroll
;       for (int i = 0; i < 4; ++i) {
;         const int id = tid + i * 256, r = id >> 3, c = (id & 7) ^ (r & 7);
;         __builtin_amdgcn_global_load_lds((const unsigned*)fa(r, kn * 8 + c), (LAS unsigned*)(dst + id * 16), 16, 0, 0);
;         __builtin_amdgcn_global_load_lds((const unsigned*)fb(r, kn * 8 + c), (LAS unsigned*)(dst + 16384 + id * 16), 16, 0, 0);
;       }
;     }
;     const char* A = lds + cur * 32768;
;     const char* B = A + 16384;
; #pragma unroll
;     for (int kk = 0; kk < 2; ++kk) {
;       bf16x8 af[4], bq[4];
; #pragma unroll
;       for (int m = 0; m < 4; ++m) af[m] = ldfrag(A, 128, wr * 64 + m * 16 + fr, kk * 4 + fq);
; #pragma unroll
;       for (int n = 0; n < 4; ++n) bq[n] = ldfrag(B, 128, wc * 64 + n * 16 + fr, kk * 4 + fq);
; #pragma unroll
;       for (int m = 0; m < 4; ++m)
; #pragma unroll
;         for (int n = 0; n < 4; ++n) acc[m][n] = MFMA16(bq[n], af[m], acc[m][n]);
;     }
;     asm volatile("s_waitcnt vmcnt(0)" ::: "memory");
;     __syncthreads();
	ds_read_b128 v[10:13], v27 offset:16384
	ds_read_b128 v[14:17], v57
	ds_read_b128 v[18:21], v27 offset:18432
	v_bitop3_b32 v159, v155, 7, v26 bitop3:0x48
	ds_read_b128 v[28:31], v57 offset:2048
	ds_read_b128 v[32:35], v27 offset:20480
	v_bitop3_b32 v160, v156, 7, v26 bitop3:0x48
	v_bitop3_b32 v161, v157, 7, v26 bitop3:0x48
	ds_read_b128 v[40:43], v27 offset:22528
	v_lshl_add_u64 v[26:27], s[12:13], 0, v[68:69]
	v_lshlrev_b32_e32 v68, 4, v158
	v_add_u32_e32 v7, 0x8000, v56
	v_lshl_add_u64 v[8:9], v[8:9], 0, v[68:69]
	v_readfirstlane_b32 s0, v7
	v_lshl_add_u64 v[8:9], v[8:9], 0, s[16:17]
	s_mov_b32 m0, s0
	v_add_u32_e32 v7, 0xc000, v56
	global_load_lds_dwordx4 v[8:9], off
	v_lshl_add_u64 v[8:9], v[22:23], 0, v[68:69]
	v_readfirstlane_b32 s0, v7
	v_add_u32_e32 v7, 0x8000, v1
	v_lshl_add_u64 v[8:9], v[8:9], 0, s[16:17]
	s_mov_b32 m0, s0
	v_readfirstlane_b32 s0, v7
	v_add_u32_e32 v1, 0xc000, v1
	global_load_lds_dwordx4 v[8:9], off
	s_mov_b32 m0, s0
	v_readfirstlane_b32 s0, v1
	v_add_u32_e32 v1, v102, v90
	v_lshlrev_b32_e32 v68, 4, v159
	v_add_u32_e32 v7, v1, v88
	ds_read_b128 v[52:55], v57 offset:4096
	ds_read_b128 v[124:127], v7 offset:16384
	ds_read_b128 v[56:59], v57 offset:6144
	v_lshl_add_u64 v[8:9], v[60:61], 0, v[68:69]
	v_lshl_add_u64 v[8:9], v[8:9], 0, s[16:17]
	global_load_lds_dwordx4 v[8:9], off
	v_lshl_add_u64 v[8:9], v[62:63], 0, v[68:69]
	v_lshl_add_u64 v[22:23], v[8:9], 0, s[16:17]
	s_mov_b32 m0, s0
	v_add_u32_e32 v1, v1, v89
	global_load_lds_dwordx4 v[22:23], off
	s_waitcnt lgkmcnt(0)
	v_mfma_f32_16x16x32_bf16 v[44:47], v[18:21], v[14:17], 0
	v_lshlrev_b32_e32 v68, 4, v160
	v_add_u32_e32 v22, 0x8000, v3
	v_add_u32_e32 v3, 0xc000, v3
	v_mfma_f32_16x16x32_bf16 v[48:51], v[32:35], v[14:17], 0
	v_readfirstlane_b32 s0, v22
	s_mov_b32 m0, s0
	v_readfirstlane_b32 s0, v3
	v_mfma_f32_16x16x32_bf16 v[92:95], v[18:21], v[28:31], 0
	v_add_u32_e32 v3, 0x8000, v5
	v_lshl_add_u32 v91, v91, 1, 4
	s_mov_b32 s37, -9
	v_mfma_f32_16x16x32_bf16 v[96:99], v[32:35], v[28:31], 0
	s_mov_b32 s38, 0
	s_mov_b32 s39, 0x8000
	v_mfma_f32_16x16x32_bf16 v[108:111], v[18:21], v[52:55], 0
	v_mfma_f32_16x16x32_bf16 v[112:115], v[32:35], v[52:55], 0
	v_mfma_f32_16x16x32_bf16 v[120:123], v[18:21], v[56:59], 0
	ds_read_b128 v[18:21], v1
	ds_read_b128 v[132:135], v7 offset:18432
	v_mfma_f32_16x16x32_bf16 v[128:131], v[32:35], v[56:59], 0
	ds_read_b128 v[32:35], v1 offset:2048
	ds_read_b128 v[140:143], v7 offset:20480
	ds_read_b128 v[144:147], v7 offset:22528
	v_mfma_f32_16x16x32_bf16 v[36:39], v[10:13], v[14:17], 0
	v_mfma_f32_16x16x32_bf16 v[72:75], v[10:13], v[28:31], 0
	v_mfma_f32_16x16x32_bf16 v[104:107], v[10:13], v[52:55], 0
	v_mfma_f32_16x16x32_bf16 v[8:11], v[10:13], v[56:59], 0
	v_lshl_add_u64 v[12:13], v[64:65], 0, v[68:69]
	v_lshl_add_u64 v[12:13], v[12:13], 0, s[16:17]
	global_load_lds_dwordx4 v[12:13], off
	v_lshl_add_u64 v[12:13], v[76:77], 0, v[68:69]
	v_mfma_f32_16x16x32_bf16 v[14:17], v[40:43], v[14:17], 0
	v_lshl_add_u64 v[12:13], v[12:13], 0, s[16:17]
	s_mov_b32 m0, s0
	v_lshlrev_b32_e32 v68, 4, v161
	global_load_lds_dwordx4 v[12:13], off
	v_lshl_add_u64 v[12:13], v[100:101], 0, v[68:69]
	v_readfirstlane_b32 s0, v3
	v_lshl_add_u64 v[12:13], v[12:13], 0, s[16:17]
	s_mov_b32 m0, s0
	v_add_u32_e32 v3, 0xc000, v5
	global_load_lds_dwordx4 v[12:13], off
	v_lshl_add_u64 v[12:13], v[148:149], 0, v[68:69]
	v_readfirstlane_b32 s0, v3
	v_mfma_f32_16x16x32_bf16 v[116:119], v[40:43], v[52:55], 0
	s_mov_b32 m0, s0
	ds_read_b128 v[148:151], v1 offset:6144
	v_lshlrev_b32_e32 v76, 10, v157
	s_waitcnt lgkmcnt(0)
	v_mfma_f32_16x16x32_bf16 v[52:55], v[144:147], v[18:21], v[14:17]
	v_mov_b32_e32 v77, v69
	v_lshlrev_b32_e32 v68, 1, v154
	v_lshl_add_u64 v[76:77], v[152:153], 0, v[76:77]
	v_lshl_add_u64 v[16:17], v[12:13], 0, s[16:17]
	global_load_lds_dwordx4 v[16:17], off
	ds_read_b128 v[12:15], v1 offset:4096
	v_mfma_f32_16x16x32_bf16 v[28:31], v[40:43], v[28:31], 0
	s_waitcnt vmcnt(0)
	v_sub_u32_e32 v100, 0, v68
	s_mov_b64 s[0:1], 0
	v_mfma_f32_16x16x32_bf16 v[136:139], v[40:43], v[56:59], 0
	s_waitcnt lgkmcnt(0)
	s_barrier
	v_mfma_f32_16x16x32_bf16 v[64:67], v[124:127], v[18:21], v[36:39]
	v_mfma_f32_16x16x32_bf16 v[60:63], v[132:135], v[18:21], v[44:47]
	v_mfma_f32_16x16x32_bf16 v[56:59], v[140:143], v[18:21], v[48:51]
	v_mfma_f32_16x16x32_bf16 v[48:51], v[124:127], v[32:35], v[72:75]
	v_mfma_f32_16x16x32_bf16 v[44:47], v[132:135], v[32:35], v[92:95]
	s_nop 1
	v_lshlrev_b32_e32 v72, 10, v155
	v_mov_b32_e32 v73, v69
	v_lshlrev_b32_e32 v74, 10, v156
	v_mfma_f32_16x16x32_bf16 v[40:43], v[140:143], v[32:35], v[96:99]
	v_lshrrev_b32_e32 v92, 4, v0
	v_lshrrev_b32_e32 v93, 4, v2
	v_lshrrev_b32_e32 v94, 4, v4
	v_mfma_f32_16x16x32_bf16 v[36:39], v[144:147], v[32:35], v[28:31]
	v_lshrrev_b32_e32 v95, 4, v6
	v_mov_b32_e32 v75, v69
	v_lshl_add_u64 v[72:73], v[152:153], 0, v[72:73]
	v_mfma_f32_16x16x32_bf16 v[32:35], v[124:127], v[12:15], v[104:107]
	v_lshl_add_u64 v[74:75], v[152:153], 0, v[74:75]
	v_lshlrev_b32_e32 v96, 3, v158
	v_lshlrev_b32_e32 v97, 3, v159
	v_mfma_f32_16x16x32_bf16 v[28:31], v[132:135], v[12:15], v[108:111]
	v_lshlrev_b32_e32 v98, 3, v160
	v_lshlrev_b32_e32 v99, 3, v161
	v_mfma_f32_16x16x32_bf16 v[20:23], v[140:143], v[12:15], v[112:115]
	v_mfma_f32_16x16x32_bf16 v[16:19], v[144:147], v[12:15], v[116:119]
	v_mfma_f32_16x16x32_bf16 v[12:15], v[124:127], v[148:151], v[8:11]
	v_mfma_f32_16x16x32_bf16 v[8:11], v[132:135], v[148:151], v[120:123]
	v_mfma_f32_16x16x32_bf16 v[4:7], v[140:143], v[148:151], v[128:131]
	v_mfma_f32_16x16x32_bf16 v[0:3], v[144:147], v[148:151], v[136:139]
	s_branch .LBB0_627
; #define MFMA16(a, b, c) __builtin_amdgcn_mfma_f32_16x16x32_bf16((a), (b), (c), 0, 0, 0)
; #define LAS __attribute__((address_space(3)))
; template <class FA, class FB, class FL, class FS>
; DI void gemm_tile(char* lds, int ksteps, int rot, FA fa, FB fb, FL fl, FS fs) {
;     ...
;   for (int ks = 0; ks < ksteps; ++ks) {
;     const int cur = ks & 1;
;     if (ks + 1 < ksteps) {
;       int kn = ks + 1 + rot; if (kn >= ksteps) kn -= ksteps;
;       LAS char* dst = l3 + (cur ^ 1) * 32768;
; #pragma unroll
;       for (int i = 0; i < 4; ++i) {
;         const int id = tid + i * 256, r = id >> 3, c = (id & 7) ^ (r & 7);
;         __builtin_amdgcn_global_load_lds((const unsigned*)fa(r, kn * 8 + c), (LAS unsigned*)(dst + id * 16), 16, 0, 0);
;         __builtin_amdgcn_global_load_lds((const unsigned*)fb(r, kn * 8 + c), (LAS unsigned*)(dst + 16384 + id * 16), 16, 0, 0);
;       }
;     }
;     const char* A = lds + cur * 32768;
;     const char* B = A + 16384;
; #pragma unroll
;     for (int kk = 0; kk < 2; ++kk) {
;       bf16x8 af[4], bq[4];
; #pragma unroll
;       for (int m = 0; m < 4; ++m) af[m] = ldfrag(A, 128, wr * 64 + m * 16 + fr, kk * 4 + fq);
; #pragma unroll
;       for (int n = 0; n < 4; ++n) bq[n] = ldfrag(B, 128, wc * 64 + n * 16 + fr, kk * 4 + fq);
; #pragma unroll
;       for (int m = 0; m < 4; ++m)
; #pragma unroll
;         for (int n = 0; n < 4; ++n) acc[m][n] = MFMA16(bq[n], af[m], acc[m][n]);
;     }
;     asm volatile("s_waitcnt vmcnt(0)" ::: "memory");
;     __syncthreads();
.LBB0_626:
	s_or_b64 exec, exec, s[2:3]
	v_add_u32_e32 v68, s40, v102
	v_add_u32_e32 v101, v68, v87
	v_add_u32_e32 v124, v101, v88
	ds_read_b128 v[104:107], v124 offset:16384
	v_add_u32_e32 v101, v101, v89
	ds_read_b128 v[108:111], v124 offset:18432
	ds_read_b128 v[112:115], v101
	ds_read_b128 v[116:119], v101 offset:2048
	ds_read_b128 v[120:123], v124 offset:20480
	ds_read_b128 v[124:127], v124 offset:22528
	s_waitcnt lgkmcnt(0)
	v_mfma_f32_16x16x32_bf16 v[60:63], v[108:111], v[112:115], v[60:63]
	v_add_u32_e32 v68, v68, v90
	s_add_i32 s37, s37, 1
	s_add_i32 s39, s39, 0x8000
	v_mfma_f32_16x16x32_bf16 v[64:67], v[104:107], v[112:115], v[64:67]
	s_add_i32 s38, s38, 64
	v_cmp_eq_u32_e32 vcc, s37, v100
	s_or_b64 s[0:1], vcc, s[0:1]
	v_mfma_f32_16x16x32_bf16 v[56:59], v[120:123], v[112:115], v[56:59]
	v_mfma_f32_16x16x32_bf16 v[52:55], v[124:127], v[112:115], v[52:55]
	v_mfma_f32_16x16x32_bf16 v[48:51], v[104:107], v[116:119], v[48:51]
	v_mfma_f32_16x16x32_bf16 v[44:47], v[108:111], v[116:119], v[44:47]
	v_mfma_f32_16x16x32_bf16 v[40:43], v[120:123], v[116:119], v[40:43]
	v_mfma_f32_16x16x32_bf16 v[36:39], v[124:127], v[116:119], v[36:39]
	ds_read_b128 v[112:115], v101 offset:4096
	ds_read_b128 v[116:119], v101 offset:6144
	v_add_u32_e32 v101, v68, v88
	v_add_u32_e32 v68, v68, v89
	s_waitcnt lgkmcnt(1)
	v_mfma_f32_16x16x32_bf16 v[32:35], v[104:107], v[112:115], v[32:35]
	v_mfma_f32_16x16x32_bf16 v[28:31], v[108:111], v[112:115], v[28:31]
	v_mfma_f32_16x16x32_bf16 v[20:23], v[120:123], v[112:115], v[20:23]
	v_mfma_f32_16x16x32_bf16 v[16:19], v[124:127], v[112:115], v[16:19]
	s_waitcnt lgkmcnt(0)
	v_mfma_f32_16x16x32_bf16 v[12:15], v[104:107], v[116:119], v[12:15]
	ds_read_b128 v[104:107], v101 offset:16384
	v_mfma_f32_16x16x32_bf16 v[8:11], v[108:111], v[116:119], v[8:11]
	v_mfma_f32_16x16x32_bf16 v[4:7], v[120:123], v[116:119], v[4:7]
	v_mfma_f32_16x16x32_bf16 v[0:3], v[124:127], v[116:119], v[0:3]
	ds_read_b128 v[108:111], v101 offset:18432
	ds_read_b128 v[112:115], v68
	ds_read_b128 v[116:119], v68 offset:2048
	ds_read_b128 v[120:123], v101 offset:20480
	ds_read_b128 v[124:127], v101 offset:22528
	s_waitcnt lgkmcnt(3)
	v_mfma_f32_16x16x32_bf16 v[64:67], v[104:107], v[112:115], v[64:67]
	v_mfma_f32_16x16x32_bf16 v[60:63], v[108:111], v[112:115], v[60:63]
	s_waitcnt lgkmcnt(1)
	v_mfma_f32_16x16x32_bf16 v[56:59], v[120:123], v[112:115], v[56:59]
	s_waitcnt lgkmcnt(0)
	v_mfma_f32_16x16x32_bf16 v[52:55], v[124:127], v[112:115], v[52:55]
	v_mfma_f32_16x16x32_bf16 v[48:51], v[104:107], v[116:119], v[48:51]
	v_mfma_f32_16x16x32_bf16 v[44:47], v[108:111], v[116:119], v[44:47]
	v_mfma_f32_16x16x32_bf16 v[40:43], v[120:123], v[116:119], v[40:43]
	v_mfma_f32_16x16x32_bf16 v[36:39], v[124:127], v[116:119], v[36:39]
	ds_read_b128 v[112:115], v68 offset:4096
	ds_read_b128 v[116:119], v68 offset:6144
	s_waitcnt vmcnt(0)
	s_waitcnt lgkmcnt(0)
	v_mfma_f32_16x16x32_bf16 v[32:35], v[104:107], v[112:115], v[32:35]
	s_barrier
	v_mfma_f32_16x16x32_bf16 v[28:31], v[108:111], v[112:115], v[28:31]
	v_mfma_f32_16x16x32_bf16 v[20:23], v[120:123], v[112:115], v[20:23]
	v_mfma_f32_16x16x32_bf16 v[16:19], v[124:127], v[112:115], v[16:19]
	v_mfma_f32_16x16x32_bf16 v[12:15], v[104:107], v[116:119], v[12:15]
	v_mfma_f32_16x16x32_bf16 v[8:11], v[108:111], v[116:119], v[8:11]
	v_mfma_f32_16x16x32_bf16 v[4:7], v[120:123], v[116:119], v[4:7]
	v_mfma_f32_16x16x32_bf16 v[0:3], v[124:127], v[116:119], v[0:3]
	s_andn2_b64 exec, exec, s[0:1]
	s_cbranch_execz .LBB0_624
